# xbar4: xbar2 + barrier TOP poll with two staggered sc1 loads in flight (no sleep between polls)
# baseline (speedup 1.0000x reference)
.Lxb_poll:
	global_load_dword v5, v193, s[4:5] sc1
	s_sleep 8
.Lxb_spin:
	global_load_dword v6, v193, s[4:5] sc1
	s_waitcnt vmcnt(1)
	v_cmp_lt_u32_e32 vcc, v5, v4
	s_and_b64 vcc, exec, vcc
	s_cbranch_vccz .Lxb_done
	global_load_dword v5, v193, s[4:5] sc1
	s_waitcnt vmcnt(1)
	v_cmp_lt_u32_e32 vcc, v6, v4
	s_and_b64 vcc, exec, vcc
	s_cbranch_vccnz .Lxb_spin
.Lxb_done:
	s_waitcnt vmcnt(0)
	buffer_inv sc1
	s_waitcnt vmcnt(0)
	s_branch .LBB0_1264
